# attention tile loops: per-interval scalar dispatch replaced by a per-wave X/Y toggle with running tile indices (about 30 fewer SALU ops and fewer branches per interval), plus pipelined conversion
# speedup vs baseline: 1.0076x; 1.0048x over previous
.LBB0_516:
	s_add_i32 s70, s68, s28
	s_lshl_b32 s30, s70, 1
	s_cmp_gt_u32 s69, 3
	s_cselect_b64 s[28:29], -1, 0
	v_cndmask_b32_e64 v0, 0, 1, s[28:29]
	v_mov_b32_e32 v14, v1
	v_mov_b32_e32 v15, v1
	v_or_b32_e32 v217, s30, v0
	v_mov_b32_e32 v0, v1
	v_mov_b32_e32 v2, v1
	v_mov_b32_e32 v3, v1
	v_mov_b32_e32 v4, v1
	v_mov_b32_e32 v5, v1
	v_mov_b32_e32 v6, v1
	v_mov_b32_e32 v7, v1
	v_mov_b32_e32 v8, v1
	v_mov_b32_e32 v9, v1
	v_mov_b32_e32 v10, v1
	v_mov_b32_e32 v11, v1
	v_mov_b32_e32 v12, v1
	v_mov_b32_e32 v13, v1
	v_mov_b64_e32 v[64:65], v[14:15]
	v_mov_b64_e32 v[48:49], v[14:15]
	v_mov_b64_e32 v[32:33], v[14:15]
	s_cmp_lt_u32 s69, 4
	v_mov_b32_e32 v240, 0
	v_mov_b64_e32 v[62:63], v[12:13]
	v_mov_b64_e32 v[60:61], v[10:11]
	v_mov_b64_e32 v[58:59], v[8:9]
	v_mov_b64_e32 v[56:57], v[6:7]
	v_mov_b64_e32 v[54:55], v[4:5]
	v_mov_b64_e32 v[52:53], v[2:3]
	v_mov_b64_e32 v[50:51], v[0:1]
	v_mov_b64_e32 v[46:47], v[12:13]
	v_mov_b64_e32 v[44:45], v[10:11]
	v_mov_b64_e32 v[42:43], v[8:9]
	v_mov_b64_e32 v[40:41], v[6:7]
	v_mov_b64_e32 v[38:39], v[4:5]
	v_mov_b64_e32 v[36:37], v[2:3]
	v_mov_b64_e32 v[34:35], v[0:1]
	v_mov_b64_e32 v[30:31], v[12:13]
	v_mov_b64_e32 v[28:29], v[10:11]
	v_mov_b64_e32 v[26:27], v[8:9]
	v_mov_b64_e32 v[24:25], v[6:7]
	v_mov_b64_e32 v[22:23], v[4:5]
	v_mov_b64_e32 v[20:21], v[2:3]
	v_mov_b64_e32 v[18:19], v[0:1]
	v_mov_b64_e32 v[16:17], v[14:15]
	s_cselect_b64 s[22:23], -1, 0
	s_mov_b32 s71, 0
	v_mov_b64_e32 v[14:15], v[12:13]
	v_mov_b64_e32 v[12:13], v[10:11]
	v_mov_b64_e32 v[10:11], v[8:9]
	v_mov_b64_e32 v[8:9], v[6:7]
	v_mov_b64_e32 v[6:7], v[4:5]
	v_mov_b64_e32 v[4:5], v[2:3]
	v_mov_b64_e32 v[2:3], v[0:1]
	v_mov_b32_e32 v239, 0
	v_mov_b32_e32 v82, 0
	v_mov_b32_e32 v83, v240
	v_mov_b32_e32 v84, v240
	v_mov_b32_e32 v85, v240
	v_mov_b32_e32 v86, v240
	v_mov_b32_e32 v87, v240
	v_mov_b32_e32 v88, v240
	v_mov_b32_e32 v89, v240
	v_mov_b32_e32 v90, v240
	v_mov_b32_e32 v91, v240
	v_mov_b32_e32 v92, v240
	v_mov_b32_e32 v93, v240
	v_mov_b32_e32 v94, v240
	v_mov_b32_e32 v95, v240
	v_mov_b32_e32 v96, v240
	v_mov_b32_e32 v97, v240
	v_mov_b32_e32 v66, v240
	v_mov_b32_e32 v67, v240
	v_mov_b32_e32 v68, v240
	v_mov_b32_e32 v69, v240
	v_mov_b32_e32 v70, v240
	v_mov_b32_e32 v71, v240
	v_mov_b32_e32 v72, v240
	v_mov_b32_e32 v73, v240
	v_mov_b32_e32 v74, v240
	v_mov_b32_e32 v75, v240
	v_mov_b32_e32 v76, v240
	v_mov_b32_e32 v77, v240
	v_mov_b32_e32 v78, v240
	v_mov_b32_e32 v79, v240
	v_mov_b32_e32 v80, v240
	v_mov_b32_e32 v81, v240
	s_cmp_gt_u32 s69, 3
	s_cselect_b32 s100, 1, 0
	s_cselect_b32 s99, -1, 0
	s_mov_b32 s98, 0
	s_branch .LBB0_518

.LBB0_518:
	s_lshr_b32 s34, s71, 1
	s_bitcmp1_b32 s71, 0
	s_cbranch_scc0 .LBB0_523
	s_cmp_gt_u32 s71, 1
	s_cbranch_scc0 .LBB0_523
	s_add_i32 s35, s34, 1
	s_cmp_ge_u32 s35, s70
	s_cbranch_scc1 .LBB0_521
	s_bitcmp1_b32 s35, 0
	s_cselect_b32 s35, 0xb400, 0
	s_add_i32 s35, s35, 0
	v_add3_u32 v0, s35, v227, v218
	s_waitcnt vmcnt(4)
	ds_write_b128 v0, v[146:149]
	v_add3_u32 v0, s35, v228, v220
	s_waitcnt vmcnt(3)
	ds_write_b128 v0, v[150:153]
	v_add3_u32 v0, s35, v229, v226
	s_waitcnt vmcnt(2)
	ds_write_b128 v0, v[154:157] offset:256
	v_add3_u32 v0, s35, v230, v218
	s_waitcnt vmcnt(1)
	ds_write_b128 v0, v[158:161] offset:25600
	v_add3_u32 v0, s35, v201, v220
	s_waitcnt vmcnt(0)
	ds_write_b128 v0, v[162:165] offset:25600

.LBB0_523:
	s_cmp_eq_u32 s100, 0
	s_cbranch_scc0 .Lyturn_M
	s_mov_b32 s100, 1
	s_cmp_ge_u32 s98, s70
	s_cbranch_scc1 .LBB0_517
	s_mov_b32 s72, s98
	s_add_i32 s98, s98, 1
	s_bitcmp1_b32 s72, 0
	s_cselect_b32 s72, 0xb400, 0
	v_add_u32_e32 v0, s72, v209
	ds_read_b128 v[166:169], v0
	ds_read_b128 v[170:173], v0 offset:32
	ds_read_b128 v[174:177], v0 offset:64
	ds_read_b128 v[178:181], v0 offset:96
	ds_read_b128 v[242:245], v0 offset:128
	ds_read_b128 v[246:249], v0 offset:160
	ds_read_b128 v[250:253], v0 offset:192
	ds_read_b128 v[204:207], v0 offset:224
	v_xor_b32_e32 v66, 0x80000000, v240
	v_mov_b32_e32 v67, v66
	v_mov_b32_e32 v68, v66
	v_mov_b32_e32 v69, v66
	v_mov_b32_e32 v70, v66
	v_mov_b32_e32 v71, v66
	v_mov_b32_e32 v72, v66
	v_mov_b32_e32 v73, v66
	v_mov_b32_e32 v74, v66
	v_mov_b32_e32 v75, v66
	v_mov_b32_e32 v76, v66
	v_mov_b32_e32 v77, v66
	v_mov_b32_e32 v78, v66
	v_mov_b32_e32 v79, v66
	v_mov_b32_e32 v80, v66
	v_mov_b32_e32 v81, v66
	s_waitcnt lgkmcnt(7)
	s_nop 0
	v_mfma_f32_32x32x16_bf16 v[82:97], v[166:169], v[98:101], v[66:81]
	s_waitcnt lgkmcnt(6)
	v_mfma_f32_32x32x16_bf16 v[82:97], v[170:173], v[102:105], v[82:97]
	s_waitcnt lgkmcnt(5)
	v_mfma_f32_32x32x16_bf16 v[82:97], v[174:177], v[106:109], v[82:97]
	s_waitcnt lgkmcnt(4)
	v_mfma_f32_32x32x16_bf16 v[82:97], v[178:181], v[110:113], v[82:97]
	ds_read_b128 v[166:169], v0 offset:256
	ds_read_b128 v[170:173], v0 offset:288
	ds_read_b128 v[174:177], v0 offset:320
	ds_read_b128 v[178:181], v0 offset:352
	s_waitcnt lgkmcnt(7)
	v_mfma_f32_32x32x16_bf16 v[82:97], v[242:245], v[114:117], v[82:97]
	s_waitcnt lgkmcnt(6)
	v_mfma_f32_32x32x16_bf16 v[82:97], v[246:249], v[118:121], v[82:97]
	s_waitcnt lgkmcnt(5)
	v_mfma_f32_32x32x16_bf16 v[82:97], v[250:253], v[122:125], v[82:97]
	s_waitcnt lgkmcnt(4)
	v_mfma_f32_32x32x16_bf16 v[82:97], v[204:207], v[126:129], v[82:97]
	ds_read_b128 v[204:207], v0 offset:12800
	ds_read_b128 v[242:245], v0 offset:12832
	ds_read_b128 v[246:249], v0 offset:12864
	ds_read_b128 v[250:253], v0 offset:12896
	s_waitcnt lgkmcnt(7)
	v_mfma_f32_32x32x16_bf16 v[82:97], v[166:169], v[130:133], v[82:97]
	s_waitcnt lgkmcnt(6)
	v_mfma_f32_32x32x16_bf16 v[82:97], v[170:173], v[134:137], v[82:97]
	s_waitcnt lgkmcnt(5)
	v_mfma_f32_32x32x16_bf16 v[82:97], v[174:177], v[138:141], v[82:97]
	s_waitcnt lgkmcnt(4)
	v_mfma_f32_32x32x16_bf16 v[82:97], v[178:181], v[142:145], v[82:97]
	ds_read_b128 v[166:169], v0 offset:12928
	ds_read_b128 v[170:173], v0 offset:12960
	ds_read_b128 v[174:177], v0 offset:12992
	ds_read_b128 v[178:181], v0 offset:13024
	s_waitcnt lgkmcnt(7)
	v_mfma_f32_32x32x16_bf16 v[66:81], v[204:207], v[98:101], v[66:81]
	s_waitcnt lgkmcnt(6)
	v_mfma_f32_32x32x16_bf16 v[66:81], v[242:245], v[102:105], v[66:81]
	s_waitcnt lgkmcnt(5)
	v_mfma_f32_32x32x16_bf16 v[66:81], v[246:249], v[106:109], v[66:81]
	s_waitcnt lgkmcnt(4)
	v_mfma_f32_32x32x16_bf16 v[66:81], v[250:253], v[110:113], v[66:81]
	ds_read_b128 v[204:207], v0 offset:13056
	ds_read_b128 v[242:245], v0 offset:13088
	ds_read_b128 v[246:249], v0 offset:13120
	ds_read_b128 v[250:253], v0 offset:13152
	s_waitcnt lgkmcnt(7)
	v_mfma_f32_32x32x16_bf16 v[66:81], v[166:169], v[114:117], v[66:81]
	s_waitcnt lgkmcnt(6)
	v_mfma_f32_32x32x16_bf16 v[66:81], v[170:173], v[118:121], v[66:81]
	s_waitcnt lgkmcnt(5)
	v_mfma_f32_32x32x16_bf16 v[66:81], v[174:177], v[122:125], v[66:81]
	s_waitcnt lgkmcnt(4)
	v_mfma_f32_32x32x16_bf16 v[66:81], v[178:181], v[126:129], v[66:81]
	s_waitcnt lgkmcnt(3)
	v_mfma_f32_32x32x16_bf16 v[66:81], v[204:207], v[130:133], v[66:81]
	s_waitcnt lgkmcnt(2)
	v_mfma_f32_32x32x16_bf16 v[66:81], v[242:245], v[134:137], v[66:81]
	s_waitcnt lgkmcnt(1)
	v_mfma_f32_32x32x16_bf16 v[66:81], v[246:249], v[138:141], v[66:81]
	s_waitcnt lgkmcnt(0)
	v_mfma_f32_32x32x16_bf16 v[66:81], v[250:253], v[142:145], v[66:81]
.LBB0_525:
	s_branch .LBB0_517
.Lyturn_M:
	s_mov_b32 s100, 0
	s_mov_b32 s34, s99
	s_add_i32 s99, s99, 1
	s_cmp_lt_i32 s34, 0
	s_cbranch_scc1 .LBB0_517
	s_cmp_ge_i32 s34, s70
	s_cbranch_scc1 .LBB0_517
	s_bitcmp1_b32 s34, 0
	s_cselect_b32 s30, 0xb400, 0
	s_setprio 2
	v_add_u32_e32 v241, s30, v233
	ds_read_b64_tr_b16 v[178:179], v241 offset:25600
	ds_read_b64_tr_b16 v[174:175], v241 offset:25664
	ds_read_b64_tr_b16 v[170:171], v241 offset:25728
	ds_read_b64_tr_b16 v[166:167], v241 offset:25792
	ds_read_b64_tr_b16 v[180:181], v241 offset:28160
	ds_read_b64_tr_b16 v[176:177], v241 offset:28224
	ds_read_b64_tr_b16 v[172:173], v241 offset:28288
	ds_read_b64_tr_b16 v[168:169], v241 offset:28352
	v_max3_f32 v0, v82, s58, v83
	v_max3_f32 v0, v0, v84, v85
	v_max3_f32 v0, v0, v86, v87
	v_max3_f32 v0, v0, v88, v89
	v_max3_f32 v0, v0, v90, v91
	v_max3_f32 v0, v0, v92, v93
	v_max3_f32 v0, v0, v94, v95
	v_max3_f32 v0, v0, v96, v97
	v_max3_f32 v0, v0, v66, v67
	v_max3_f32 v0, v0, v68, v69
	v_max3_f32 v0, v0, v70, v71
	v_max3_f32 v0, v0, v72, v73
	v_max3_f32 v0, v0, v74, v75
	v_max3_f32 v0, v0, v76, v77
	v_max3_f32 v0, v0, v78, v79
	v_max3_f32 v0, v0, v80, v81
	v_mov_b32_e32 v194, v0
	s_nop 1
	v_permlane32_swap_b32 v194, v0
	s_nop 1
	s_cmp_lg_u32 s34, 0
	v_max_f32_e32 v0, v0, v0
	v_max_f32_e32 v194, v194, v194
	s_cselect_b64 s[30:31], -1, 0
	s_cmp_eq_u32 s34, 0
	v_max_f32_e32 v0, v194, v0
	s_cbranch_scc1 .LBB0_529
	v_cmp_ge_f32_e32 vcc, s59, v0
	s_cmp_lg_u64 vcc, exec
	s_mov_b64 s[34:35], 0
	s_cbranch_scc0 .LBB0_530
	v_max_f32_e32 v0, v0, v0
	v_max_f32_e32 v0, 0, v0

.LBB0_792:
	s_lshl_b32 s29, s72, 1
	s_cmp_gt_u32 s71, 3
	s_cselect_b64 s[26:27], -1, 0
	v_cndmask_b32_e64 v0, 0, 1, s[26:27]
	s_cmp_lt_u32 s71, 4
	v_readfirstlane_b32 s30, v0
	s_cselect_b64 s[18:19], -1, 0
	s_or_b32 s73, s29, s30
	s_cmp_lt_i32 s73, 1
	s_cbranch_scc1 .LBB0_815
	v_or_b32_e32 v0, s28, v2
	v_mov_b32_e32 v14, v1
	v_mov_b32_e32 v15, v1
	v_sub_u32_e32 v135, v124, v0
	v_mov_b32_e32 v0, v1
	v_mov_b32_e32 v2, v1
	v_mov_b32_e32 v3, v1
	v_mov_b32_e32 v4, v1
	v_mov_b32_e32 v5, v1
	v_mov_b32_e32 v6, v1
	v_mov_b32_e32 v7, v1
	v_mov_b32_e32 v8, v1
	v_mov_b32_e32 v9, v1
	v_mov_b32_e32 v10, v1
	v_mov_b32_e32 v11, v1
	v_mov_b32_e32 v12, v1
	v_mov_b32_e32 v13, v1
	v_mov_b32_e32 v48, 0
	v_mov_b64_e32 v[46:47], v[14:15]
	v_mov_b64_e32 v[30:31], v[14:15]
	s_mov_b32 s77, 0
	v_mov_b64_e32 v[44:45], v[12:13]
	v_mov_b64_e32 v[42:43], v[10:11]
	v_mov_b64_e32 v[40:41], v[8:9]
	v_mov_b64_e32 v[38:39], v[6:7]
	v_mov_b64_e32 v[36:37], v[4:5]
	v_mov_b64_e32 v[34:35], v[2:3]
	v_mov_b64_e32 v[32:33], v[0:1]
	v_mov_b64_e32 v[28:29], v[12:13]
	v_mov_b64_e32 v[26:27], v[10:11]
	v_mov_b64_e32 v[24:25], v[8:9]
	v_mov_b64_e32 v[22:23], v[6:7]
	v_mov_b64_e32 v[20:21], v[4:5]
	v_mov_b64_e32 v[18:19], v[2:3]
	v_mov_b64_e32 v[16:17], v[0:1]
	v_mov_b32_e32 v49, v48
	v_mov_b32_e32 v50, v48
	v_mov_b32_e32 v51, v48
	v_mov_b32_e32 v52, v48
	v_mov_b32_e32 v53, v48
	v_mov_b32_e32 v54, v48
	v_mov_b32_e32 v55, v48
	v_mov_b32_e32 v56, v48
	v_mov_b32_e32 v57, v48
	v_mov_b32_e32 v58, v48
	v_mov_b32_e32 v59, v48
	v_mov_b32_e32 v60, v48
	v_mov_b32_e32 v61, v48
	v_mov_b32_e32 v62, v48
	v_mov_b32_e32 v63, v48
	v_mov_b32_e32 v64, v48
	v_mov_b32_e32 v65, v48
	v_mov_b32_e32 v66, v48
	v_mov_b32_e32 v67, v48
	v_mov_b32_e32 v68, v48
	v_mov_b32_e32 v69, v48
	v_mov_b32_e32 v70, v48
	v_mov_b32_e32 v71, v48
	v_mov_b32_e32 v72, v48
	v_mov_b32_e32 v73, v48
	v_mov_b32_e32 v74, v48
	v_mov_b32_e32 v75, v48
	v_mov_b32_e32 v76, v48
	v_mov_b32_e32 v77, v48
	v_mov_b32_e32 v78, v48
	v_mov_b32_e32 v79, v48
	s_cmp_gt_u32 s71, 3
	s_cselect_b32 s100, 1, 0
	s_cselect_b32 s99, -1, 0
	s_mov_b32 s98, 0
	s_branch .LBB0_795

.LBB0_795:
	s_lshr_b32 s78, s77, 1
	s_bitcmp1_b32 s77, 0
	s_cbranch_scc0 .LBB0_800
	s_cmp_gt_u32 s77, 1
	s_cbranch_scc0 .LBB0_800
	s_add_i32 s30, s78, 1
	s_cmp_ge_i32 s30, s72
	s_cbranch_scc1 .LBB0_798
	s_bitcmp1_b32 s30, 0
	s_cselect_b32 s30, 0x5400, 0
	s_add_i32 s30, s30, 0
	v_add3_u32 v2, s30, v121, v120
	v_add3_u32 v0, s30, v123, v120
	s_waitcnt vmcnt(1)
	ds_write_b128 v2, v[96:99]
	s_waitcnt vmcnt(0)
	ds_write_b128 v0, v[100:103] offset:9216

.LBB0_800:
	s_cmp_eq_u32 s100, 0
	s_cbranch_scc0 .Lyturn_W
	s_mov_b32 s100, 1
	s_cmp_ge_u32 s98, s72
	s_cbranch_scc1 .LBB0_794
	s_mov_b32 s80, s98
	s_add_i32 s98, s98, 1
	s_bitcmp1_b32 s80, 0
	s_cselect_b32 s30, 0x5400, 0
	v_add_u32_e32 v0, s30, v113
	ds_read_b128 v[2:5], v0
	ds_read_b128 v[6:9], v0 offset:32
	ds_read_b128 v[10:13], v0 offset:64
	ds_read_b128 v[136:139], v0 offset:96
	ds_read_b128 v[140:143], v0 offset:4608
	ds_read_b128 v[144:147], v0 offset:4640
	ds_read_b128 v[148:151], v0 offset:4672
	ds_read_b128 v[152:155], v0 offset:4704
	v_xor_b32_e32 v64, 0x80000000, v134
	v_mov_b32_e32 v65, v64
	v_mov_b32_e32 v66, v64
	v_mov_b32_e32 v67, v64
	v_mov_b32_e32 v68, v64
	v_mov_b32_e32 v69, v64
	v_mov_b32_e32 v70, v64
	v_mov_b32_e32 v71, v64
	v_mov_b32_e32 v72, v64
	v_mov_b32_e32 v73, v64
	v_mov_b32_e32 v74, v64
	v_mov_b32_e32 v75, v64
	v_mov_b32_e32 v76, v64
	v_mov_b32_e32 v77, v64
	v_mov_b32_e32 v78, v64
	v_mov_b32_e32 v79, v64
	s_waitcnt lgkmcnt(7)
	s_nop 0
	v_mfma_f32_32x32x16_bf16 v[48:63], v[2:5], v[80:83], v[64:79]
	s_waitcnt lgkmcnt(6)
	v_mfma_f32_32x32x16_bf16 v[48:63], v[6:9], v[84:87], v[48:63]
	s_waitcnt lgkmcnt(5)
	v_mfma_f32_32x32x16_bf16 v[48:63], v[10:13], v[88:91], v[48:63]
	s_waitcnt lgkmcnt(4)
	v_mfma_f32_32x32x16_bf16 v[48:63], v[136:139], v[92:95], v[48:63]
	s_waitcnt lgkmcnt(3)
	v_mfma_f32_32x32x16_bf16 v[64:79], v[140:143], v[80:83], v[64:79]
	s_waitcnt lgkmcnt(2)
	v_mfma_f32_32x32x16_bf16 v[64:79], v[144:147], v[84:87], v[64:79]
	s_waitcnt lgkmcnt(1)
	v_mfma_f32_32x32x16_bf16 v[64:79], v[148:151], v[88:91], v[64:79]
	s_waitcnt lgkmcnt(0)
	v_mfma_f32_32x32x16_bf16 v[64:79], v[152:155], v[92:95], v[64:79]
	s_cmp_lt_u32 s80, 4
	s_cselect_b64 s[30:31], -1, 0
	s_and_b64 s[82:83], s[30:31], exec
	s_cselect_b32 s81, -1, s70
	s_cmp_lt_i32 s81, 0
	s_cbranch_scc1 .LBB0_803
	s_and_b64 s[30:31], s[30:31], exec
	s_cselect_b32 s30, 0, -4
	s_add_i32 s30, s30, s80
	s_lshl_b32 s30, s30, 6
	s_add_i32 s30, s30, s81
	v_add_u32_e32 v0, s30, v135
	s_movk_i32 s30, 0xfeff
	v_cmp_gt_u32_e32 vcc, s30, v0
	v_add_u32_e32 v2, 1, v0
	s_nop 0
	v_cndmask_b32_e32 v48, v48, v225, vcc
	v_cmp_lt_u32_e32 vcc, s60, v2
	v_add_u32_e32 v2, 2, v0
	s_nop 0
	v_cndmask_b32_e32 v49, v225, v49, vcc
	v_cmp_lt_u32_e32 vcc, s60, v2
	v_add_u32_e32 v2, 3, v0
	s_nop 0
	v_cndmask_b32_e32 v50, v225, v50, vcc
	v_cmp_lt_u32_e32 vcc, s60, v2
	v_add_u32_e32 v2, 8, v0
	s_nop 0
	v_cndmask_b32_e32 v51, v225, v51, vcc
	v_cmp_lt_u32_e32 vcc, s60, v2
	v_add_u32_e32 v2, 9, v0
	s_nop 0
	v_cndmask_b32_e32 v52, v225, v52, vcc
	v_cmp_lt_u32_e32 vcc, s60, v2
	v_add_u32_e32 v2, 10, v0
	s_nop 0
	v_cndmask_b32_e32 v53, v225, v53, vcc
	v_cmp_lt_u32_e32 vcc, s60, v2
	v_add_u32_e32 v2, 11, v0
	s_nop 0
	v_cndmask_b32_e32 v54, v225, v54, vcc
	v_cmp_lt_u32_e32 vcc, s60, v2
	v_add_u32_e32 v2, 16, v0
	s_nop 0
	v_cndmask_b32_e32 v55, v225, v55, vcc
	v_cmp_lt_u32_e32 vcc, s60, v2
	v_add_u32_e32 v2, 17, v0
	s_nop 0
	v_cndmask_b32_e32 v56, v225, v56, vcc
	v_cmp_lt_u32_e32 vcc, s60, v2
	v_add_u32_e32 v2, 18, v0
	s_nop 0
	v_cndmask_b32_e32 v57, v225, v57, vcc
	v_cmp_lt_u32_e32 vcc, s60, v2
	v_add_u32_e32 v2, 19, v0
	s_nop 0
	v_cndmask_b32_e32 v58, v225, v58, vcc
	v_cmp_lt_u32_e32 vcc, s60, v2
	v_add_u32_e32 v2, 24, v0
	s_nop 0
	v_cndmask_b32_e32 v59, v225, v59, vcc
	v_cmp_lt_u32_e32 vcc, s60, v2
	v_add_u32_e32 v2, 25, v0
	s_nop 0
	v_cndmask_b32_e32 v60, v225, v60, vcc
	v_cmp_lt_u32_e32 vcc, s60, v2
	v_add_u32_e32 v2, 26, v0
	s_nop 0
	v_cndmask_b32_e32 v61, v225, v61, vcc
	v_cmp_lt_u32_e32 vcc, s60, v2
	v_add_u32_e32 v2, 27, v0
	s_nop 0
	v_cndmask_b32_e32 v62, v225, v62, vcc
	v_cmp_lt_u32_e32 vcc, s60, v2
	v_add_u32_e32 v2, 32, v0
	s_nop 0
	v_cndmask_b32_e32 v63, v225, v63, vcc
	v_cmp_lt_u32_e32 vcc, s60, v2
	v_add_u32_e32 v2, 33, v0
	s_nop 0
	v_cndmask_b32_e32 v64, v225, v64, vcc
	v_cmp_lt_u32_e32 vcc, s60, v2
	v_add_u32_e32 v2, 34, v0
	s_nop 0
	v_cndmask_b32_e32 v65, v225, v65, vcc
	v_cmp_lt_u32_e32 vcc, s60, v2
	v_add_u32_e32 v2, 35, v0
	s_nop 0
	v_cndmask_b32_e32 v66, v225, v66, vcc
	v_cmp_lt_u32_e32 vcc, s60, v2
	v_add_u32_e32 v2, 40, v0
	s_nop 0
	v_cndmask_b32_e32 v67, v225, v67, vcc
	v_cmp_lt_u32_e32 vcc, s60, v2
	v_add_u32_e32 v2, 41, v0
	s_nop 0
	v_cndmask_b32_e32 v68, v225, v68, vcc
	v_cmp_lt_u32_e32 vcc, s60, v2
	v_add_u32_e32 v2, 42, v0
	s_nop 0
	v_cndmask_b32_e32 v69, v225, v69, vcc
	v_cmp_lt_u32_e32 vcc, s60, v2
	v_add_u32_e32 v2, 43, v0
	s_nop 0
	v_cndmask_b32_e32 v70, v225, v70, vcc
	v_cmp_lt_u32_e32 vcc, s60, v2
	v_add_u32_e32 v2, 48, v0
	s_nop 0
	v_cndmask_b32_e32 v71, v225, v71, vcc
	v_cmp_lt_u32_e32 vcc, s60, v2
	v_add_u32_e32 v2, 49, v0
	s_nop 0
	v_cndmask_b32_e32 v72, v225, v72, vcc
	v_cmp_lt_u32_e32 vcc, s60, v2
	v_add_u32_e32 v2, 50, v0
	s_nop 0
	v_cndmask_b32_e32 v73, v225, v73, vcc
	v_cmp_lt_u32_e32 vcc, s60, v2
	v_add_u32_e32 v2, 51, v0
	s_nop 0
	v_cndmask_b32_e32 v74, v225, v74, vcc
	v_cmp_lt_u32_e32 vcc, s60, v2
	v_add_u32_e32 v2, 56, v0
	s_nop 0
	v_cndmask_b32_e32 v75, v225, v75, vcc
	v_cmp_lt_u32_e32 vcc, s60, v2
	v_add_u32_e32 v2, 57, v0
	s_nop 0
	v_cndmask_b32_e32 v76, v225, v76, vcc
	v_cmp_lt_u32_e32 vcc, s60, v2
	v_add_u32_e32 v2, 58, v0
	v_add_u32_e32 v0, 59, v0
	v_cndmask_b32_e32 v77, v225, v77, vcc
	v_cmp_lt_u32_e32 vcc, s60, v2
	s_nop 1
	v_cndmask_b32_e32 v78, v225, v78, vcc
	v_cmp_lt_u32_e32 vcc, s60, v0
	s_nop 1
	v_cndmask_b32_e32 v79, v225, v79, vcc

.Lyturn_W:
	s_mov_b32 s100, 0
	s_mov_b32 s28, s99
	s_add_i32 s99, s99, 1
	s_cmp_lt_i32 s28, 0
	s_cbranch_scc1 .LBB0_794
	s_cmp_ge_i32 s28, s72
	s_cbranch_scc1 .LBB0_794
	s_bitcmp1_b32 s28, 0
	s_cselect_b32 s29, 0x5400, 0
	s_setprio 2
	v_add_u32_e32 v10, s29, v132
	ds_read_b64_tr_b16 v[6:7], v10 offset:9216
	ds_read_b64_tr_b16 v[8:9], v10 offset:10752
	ds_read_b64_tr_b16 v[4:5], v10 offset:10816
	ds_read_b64_tr_b16 v[2:3], v10 offset:9280
	v_max3_f32 v0, v48, s58, v49
	v_max3_f32 v0, v0, v50, v51
	v_max3_f32 v0, v0, v52, v53
	v_max3_f32 v0, v0, v54, v55
	v_max3_f32 v0, v0, v56, v57
	v_max3_f32 v0, v0, v58, v59
	v_max3_f32 v0, v0, v60, v61
	v_max3_f32 v0, v0, v62, v63
	v_max3_f32 v0, v0, v64, v65
	v_max3_f32 v0, v0, v66, v67
	v_max3_f32 v0, v0, v68, v69
	v_max3_f32 v0, v0, v70, v71
	v_max3_f32 v0, v0, v72, v73
	v_max3_f32 v0, v0, v74, v75
	v_max3_f32 v0, v0, v76, v77
	v_max3_f32 v0, v0, v78, v79
	v_mov_b32_e32 v11, v0
	s_cmp_eq_u32 s28, 0
	s_nop 1
	v_permlane32_swap_b32 v0, v11
	s_nop 1
	s_cselect_b64 s[28:29], -1, 0
	v_max_f32_e32 v11, v11, v11
	v_max_f32_e32 v0, v0, v0
	s_and_b64 s[28:29], s[20:21], s[28:29]
	v_max_f32_e32 v0, v0, v11
	s_mov_b64 s[30:31], -1
	s_and_b64 vcc, exec, s[28:29]
	s_cbranch_vccnz .LBB0_807
	v_cmp_ge_f32_e32 vcc, s59, v0
	s_cmp_lg_u64 vcc, exec
	s_mov_b64 s[30:31], 0
	s_cbranch_scc0 .LBB0_807
	v_max_f32_e32 v0, v0, v0
	v_max_f32_e32 v0, 0, v0
	s_mov_b64 s[30:31], -1
